# down-proj K-loop: one extra LDS-DMA per wave per K-iter streams the X residual tile toward cache ahead of the epilogue (vmcnt 8->9 on two waits)
# speedup vs baseline: 1.0039x; 1.0039x over previous
; #define PG8_STAGE(bufoff, gbase, voff) do { _Pragma("unroll") for (int _i = 0; _i < 2; ++_i) \
;         __builtin_amdgcn_global_load_lds((const unsigned*)((const char*)(gbase) + (voff)[_i]), (LAS unsigned*)(lds + (bufoff) + ldsw + _i * 8192), 16, 0, 0); } while (0)
; #define PG8_LDA(dst, b, h) do { _Pragma("unroll") for (int m = 0; m < 4; ++m) _Pragma("unroll") for (int k = 0; k < 2; ++k) dst[m][k] = *(const LAS bf16x8*)(lds + PG8_SA(b, h) + aoff + m * 2048 + k * 1024); } while (0)
; #define PG8_LDB(dst, b, h) do { _Pragma("unroll") for (int n = 0; n < 2; ++n) _Pragma("unroll") for (int k = 0; k < 2; ++k) dst[n][k] = *(const LAS bf16x8*)(lds + PG8_SB(b, h) + boff + n * 2048 + k * 1024); } while (0)
; #define PG8_MMA(ai, bj, At, Bt) do { __builtin_amdgcn_s_setprio(1); _Pragma("unroll") for (int m = 0; m < 4; ++m) _Pragma("unroll") for (int n = 0; n < 2; ++n) _Pragma("unroll") for (int k = 0; k < 2; ++k) \
;         acc[ai][bj][m][n] = __builtin_amdgcn_mfma_f32_16x16x32_bf16(Bt[n][k], At[m][k], acc[ai][bj][m][n], 0, 0, 0); __builtin_amdgcn_s_setprio(0); } while (0)
; #define PG8_WAIT_V(n) asm volatile("s_waitcnt vmcnt(" #n ")" ::: "memory")
; #define PG8_WAIT_L(n) asm volatile("s_waitcnt lgkmcnt(" #n ")" ::: "memory")
; #define PG8_BAR __builtin_amdgcn_s_barrier()
; #define PG8_SCHED __builtin_amdgcn_sched_barrier(0)
; template <class Epi, bool ALIGN_EPI>
; __device__ __forceinline__ void gemm_phase(LAS unsigned char* lds, const Gemm g, int G, int cid, const Epi& E) {
;     ...
;             PG8_LDB(B0, 0, 0); PG8_LDB(B1, 0, 1); PG8_SCHED; PG8_LDA(At, 0, 0); PG8_STAGE(PG8_SA(1, 1), a1 + hA, voffA);
;             PG8_WAIT_V(8); PG8_WAIT_L(0); PG8_BAR; PG8_MMA(0, 0, At, B0); PG8_MMA(0, 1, At, B1); PG8_BAR; PG8_SCHED;
;     ...
;         for (int a = 0; a < 2; ++a)
; #pragma unroll
;             for (int b = 0; b < 2; ++b)
; #pragma unroll
;                 for (int m = 0; m < 4; ++m)
; #pragma unroll
;                     for (int n = 0; n < 2; ++n) acc[a][b][m][n] = (f32x4){0.f, 0.f, 0.f, 0.f};
;         cur = nxt; cA = nA; cB = nB; ++ui;
.LBB0_926:
	s_and_b32 s30, s72, 0x7fffffff
	s_lshl_b64 s[6:7], s[30:31], 14
	s_add_u32 s46, s1, s6
	s_addc_u32 s47, s24, s7
	s_and_b64 s[6:7], s[40:41], exec
	s_cselect_b32 s30, s47, s51
	s_cselect_b32 s76, s46, s50
	s_add_u32 s77, s50, 0x80000
	v_mov_b32_e32 v0, 0
	s_addc_u32 s78, s51, 0
	s_mov_b32 s79, -2
	s_waitcnt lgkmcnt(0)
	v_mov_b32_e32 v1, v0
	v_mov_b32_e32 v2, v0
	v_mov_b32_e32 v3, v0
	v_mov_b32_e32 v4, v0
	v_mov_b32_e32 v5, v0
	v_mov_b32_e32 v6, v0
	v_mov_b32_e32 v7, v0
	v_mov_b32_e32 v16, v0
	v_mov_b32_e32 v17, v0
	v_mov_b32_e32 v18, v0
	v_mov_b32_e32 v19, v0
	v_mov_b32_e32 v20, v0
	v_mov_b32_e32 v21, v0
	v_mov_b32_e32 v22, v0
	v_mov_b32_e32 v23, v0
	v_mov_b32_e32 v32, v0
	v_mov_b32_e32 v33, v0
	v_mov_b32_e32 v34, v0
	v_mov_b32_e32 v35, v0
	v_mov_b32_e32 v36, v0
	v_mov_b32_e32 v37, v0
	v_mov_b32_e32 v38, v0
	v_mov_b32_e32 v39, v0
	v_mov_b32_e32 v48, v0
	v_mov_b32_e32 v49, v0
	v_mov_b32_e32 v50, v0
	v_mov_b32_e32 v51, v0
	v_mov_b32_e32 v52, v0
	v_mov_b32_e32 v53, v0
	v_mov_b32_e32 v54, v0
	v_mov_b32_e32 v55, v0
	v_mov_b32_e32 v8, v0
	v_mov_b32_e32 v9, v0
	v_mov_b32_e32 v10, v0
	v_mov_b32_e32 v11, v0
	v_mov_b32_e32 v12, v0
	v_mov_b32_e32 v13, v0
	v_mov_b32_e32 v14, v0
	v_mov_b32_e32 v15, v0
	v_mov_b32_e32 v24, v0
	v_mov_b32_e32 v25, v0
	v_mov_b32_e32 v26, v0
	v_mov_b32_e32 v27, v0
	v_mov_b32_e32 v28, v0
	v_mov_b32_e32 v29, v0
	v_mov_b32_e32 v30, v0
	v_mov_b32_e32 v31, v0
	v_mov_b32_e32 v40, v0
	v_mov_b32_e32 v41, v0
	v_mov_b32_e32 v42, v0
	v_mov_b32_e32 v43, v0
	v_mov_b32_e32 v44, v0
	v_mov_b32_e32 v45, v0
	v_mov_b32_e32 v46, v0
	v_mov_b32_e32 v47, v0
	v_mov_b32_e32 v56, v0
	v_mov_b32_e32 v57, v0
	v_mov_b32_e32 v58, v0
	v_mov_b32_e32 v59, v0
	v_mov_b32_e32 v60, v0
	v_mov_b32_e32 v61, v0
	v_mov_b32_e32 v62, v0
	v_mov_b32_e32 v63, v0
	v_mov_b32_e32 v64, v0
	v_mov_b32_e32 v65, v0
	v_mov_b32_e32 v66, v0
	v_mov_b32_e32 v67, v0
	v_mov_b32_e32 v68, v0
	v_mov_b32_e32 v69, v0
	v_mov_b32_e32 v70, v0
	v_mov_b32_e32 v71, v0
	v_mov_b32_e32 v80, v0
	v_mov_b32_e32 v81, v0
	v_mov_b32_e32 v82, v0
	v_mov_b32_e32 v83, v0
	v_mov_b32_e32 v84, v0
	v_mov_b32_e32 v85, v0
	v_mov_b32_e32 v86, v0
	v_mov_b32_e32 v87, v0
	v_mov_b32_e32 v96, v0
	v_mov_b32_e32 v97, v0
	v_mov_b32_e32 v98, v0
	v_mov_b32_e32 v99, v0
	v_mov_b32_e32 v100, v0
	v_mov_b32_e32 v101, v0
	v_mov_b32_e32 v102, v0
	v_mov_b32_e32 v103, v0
	v_mov_b32_e32 v112, v0
	v_mov_b32_e32 v113, v0
	v_mov_b32_e32 v114, v0
	v_mov_b32_e32 v115, v0
	v_mov_b32_e32 v116, v0
	v_mov_b32_e32 v117, v0
	v_mov_b32_e32 v118, v0
	v_mov_b32_e32 v119, v0
	v_mov_b32_e32 v72, v0
	v_mov_b32_e32 v73, v0
	v_mov_b32_e32 v74, v0
	v_mov_b32_e32 v75, v0
	v_mov_b32_e32 v76, v0
	v_mov_b32_e32 v77, v0
	v_mov_b32_e32 v78, v0
	v_mov_b32_e32 v79, v0
	v_mov_b32_e32 v88, v0
	v_mov_b32_e32 v89, v0
	v_mov_b32_e32 v90, v0
	v_mov_b32_e32 v91, v0
	v_mov_b32_e32 v92, v0
	v_mov_b32_e32 v93, v0
	v_mov_b32_e32 v94, v0
	v_mov_b32_e32 v95, v0
	v_mov_b32_e32 v104, v0
	v_mov_b32_e32 v105, v0
	v_mov_b32_e32 v106, v0
	v_mov_b32_e32 v107, v0
	v_mov_b32_e32 v108, v0
	v_mov_b32_e32 v109, v0
	v_mov_b32_e32 v110, v0
	v_mov_b32_e32 v111, v0
	v_mov_b32_e32 v120, v0
	v_mov_b32_e32 v121, v0
	v_mov_b32_e32 v122, v0
	v_mov_b32_e32 v123, v0
	v_mov_b32_e32 v124, v0
	v_mov_b32_e32 v125, v0
	v_mov_b32_e32 v126, v0
	v_mov_b32_e32 v127, v0
	v_mbcnt_lo_u32_b32 v226, -1, 0
	v_mbcnt_hi_u32_b32 v226, -1, v226
	v_lshlrev_b32_e32 v226, 4, v226
.LBB0_927:
	s_add_u32 s40, s48, 0x100
	s_addc_u32 s41, s49, 0
	s_add_i32 s6, 0, 0x10000
	s_cmpk_eq_i32 s79, 0x54
	s_cselect_b32 s53, s45, s41
	s_cselect_b32 s52, s44, s40
	s_cselect_b32 s51, s30, s78
	s_cselect_b32 s50, s76, s77
	s_add_i32 s86, 0, 0x14000
	v_add_u32_e32 v144, s6, v243
	v_add_u32_e32 v160, s86, v243
	ds_read_b128 v[128:131], v144
	ds_read_b128 v[132:135], v144 offset:1024
	ds_read_b128 v[140:143], v144 offset:2048
	ds_read_b128 v[144:147], v144 offset:3072
	ds_read_b128 v[148:151], v160
	ds_read_b128 v[152:155], v160 offset:1024
	ds_read_b128 v[156:159], v160 offset:2048
	ds_read_b128 v[160:163], v160 offset:3072
	v_lshl_add_u64 v[198:199], s[48:49], 0, v[210:211]
	s_add_i32 m0, s12, 0xc000
	ds_read_b128 v[164:167], v245
	ds_read_b128 v[168:171], v245 offset:1024
	ds_read_b128 v[172:175], v245 offset:2048
	ds_read_b128 v[176:179], v245 offset:3072
	ds_read_b128 v[180:183], v245 offset:4096
	ds_read_b128 v[184:187], v245 offset:5120
	ds_read_b128 v[188:191], v245 offset:6144
	ds_read_b128 v[214:217], v245 offset:7168
	global_load_lds_dwordx4 v[198:199], off
	v_lshl_add_u64 v[198:199], s[48:49], 0, v[212:213]
	s_add_i32 m0, s12, 0xe000
	s_nop 0
	global_load_lds_dwordx4 v[198:199], off
	s_add_i32 vcc_lo, s79, 2
	s_lshl_b32 vcc_lo, vcc_lo, 15
	s_and_b32 vcc_lo, vcc_lo, 0x1f0000
	s_lshl_b32 vcc_hi, s75, 21
	s_add_i32 vcc_lo, vcc_lo, vcc_hi
	s_lshl_b32 vcc_hi, s25, 3
	s_add_i32 vcc_lo, vcc_lo, vcc_hi
	s_lshl_b32 vcc_hi, s74, 10
	s_add_i32 vcc_lo, vcc_lo, vcc_hi
	s_add_u32 vcc_lo, s82, vcc_lo
	s_addc_u32 vcc_hi, s83, 0
	s_mov_b32 m0, 0x22c00
	s_nop 0
	global_load_lds_dwordx4 v226, vcc
	s_waitcnt vmcnt(9)
	s_waitcnt lgkmcnt(0)
	s_barrier
; #define PG8_STAGE(bufoff, gbase, voff) do { _Pragma("unroll") for (int _i = 0; _i < 2; ++_i) \
;         __builtin_amdgcn_global_load_lds((const unsigned*)((const char*)(gbase) + (voff)[_i]), (LAS unsigned*)(lds + (bufoff) + ldsw + _i * 8192), 16, 0, 0); } while (0)
; #define PG8_LDA(dst, b, h) do { _Pragma("unroll") for (int m = 0; m < 4; ++m) _Pragma("unroll") for (int k = 0; k < 2; ++k) dst[m][k] = *(const LAS bf16x8*)(lds + PG8_SA(b, h) + aoff + m * 2048 + k * 1024); } while (0)
; #define PG8_MMA(ai, bj, At, Bt) do { __builtin_amdgcn_s_setprio(1); _Pragma("unroll") for (int m = 0; m < 4; ++m) _Pragma("unroll") for (int n = 0; n < 2; ++n) _Pragma("unroll") for (int k = 0; k < 2; ++k) \
;         acc[ai][bj][m][n] = __builtin_amdgcn_mfma_f32_16x16x32_bf16(Bt[n][k], At[m][k], acc[ai][bj][m][n], 0, 0, 0); __builtin_amdgcn_s_setprio(0); } while (0)
; #define PG8_WAIT_V(n) asm volatile("s_waitcnt vmcnt(" #n ")" ::: "memory")
; #define PG8_WAIT_L(n) asm volatile("s_waitcnt lgkmcnt(" #n ")" ::: "memory")
; #define PG8_BAR __builtin_amdgcn_s_barrier()
; #define PG8_SCHED __builtin_amdgcn_sched_barrier(0)
; template <class Epi, bool ALIGN_EPI>
; __device__ __forceinline__ void gemm_phase(LAS unsigned char* lds, const Gemm g, int G, int cid, const Epi& E) {
;     ...
;             PG8_WAIT_V(8); PG8_WAIT_L(0); PG8_BAR; PG8_MMA(0, 0, At, B0); PG8_MMA(0, 1, At, B1); PG8_BAR; PG8_SCHED;
;             PG8_LDA(At, 0, 1); PG8_STAGE(PG8_SB(0, 0), b2, voffB); PG8_STAGE(PG8_SB(0, 1), b2 + hB, voffB); PG8_STAGE(PG8_SA(0, 0), a2, voffA);
;             PG8_WAIT_V(8); PG8_WAIT_L(0); PG8_BAR; PG8_MMA(1, 0, At, B0); PG8_MMA(1, 1, At, B1); PG8_BAR; PG8_SCHED;
	s_setprio 1
	s_waitcnt lgkmcnt(0)
	v_mfma_f32_16x16x32_bf16 v[124:127], v[128:131], v[164:167], v[124:127]
	v_mfma_f32_16x16x32_bf16 v[120:123], v[140:143], v[164:167], v[120:123]
	v_mfma_f32_16x16x32_bf16 v[108:111], v[128:131], v[172:175], v[108:111]
	v_mfma_f32_16x16x32_bf16 v[104:107], v[140:143], v[172:175], v[104:107]
	v_mfma_f32_16x16x32_bf16 v[92:95], v[128:131], v[180:183], v[92:95]
	v_mfma_f32_16x16x32_bf16 v[88:91], v[140:143], v[180:183], v[88:91]
	v_mfma_f32_16x16x32_bf16 v[76:79], v[128:131], v[188:191], v[76:79]
	v_mfma_f32_16x16x32_bf16 v[72:75], v[140:143], v[188:191], v[72:75]
	v_mfma_f32_16x16x32_bf16 v[124:127], v[132:135], v[168:171], v[124:127]
	v_mfma_f32_16x16x32_bf16 v[120:123], v[144:147], v[168:171], v[120:123]
	v_mfma_f32_16x16x32_bf16 v[108:111], v[132:135], v[176:179], v[108:111]
	v_mfma_f32_16x16x32_bf16 v[104:107], v[144:147], v[176:179], v[104:107]
	v_mfma_f32_16x16x32_bf16 v[92:95], v[132:135], v[184:187], v[92:95]
	v_mfma_f32_16x16x32_bf16 v[88:91], v[144:147], v[184:187], v[88:91]
	v_mfma_f32_16x16x32_bf16 v[76:79], v[132:135], v[214:217], v[76:79]
	v_mfma_f32_16x16x32_bf16 v[72:75], v[144:147], v[214:217], v[72:75]
	s_setprio 0
	s_setprio 1
	v_mfma_f32_16x16x32_bf16 v[116:119], v[148:151], v[164:167], v[116:119]
	v_mfma_f32_16x16x32_bf16 v[112:115], v[156:159], v[164:167], v[112:115]
	v_mfma_f32_16x16x32_bf16 v[100:103], v[148:151], v[172:175], v[100:103]
	v_mfma_f32_16x16x32_bf16 v[96:99], v[156:159], v[172:175], v[96:99]
	v_mfma_f32_16x16x32_bf16 v[84:87], v[148:151], v[180:183], v[84:87]
	v_mfma_f32_16x16x32_bf16 v[80:83], v[156:159], v[180:183], v[80:83]
	v_mfma_f32_16x16x32_bf16 v[68:71], v[148:151], v[188:191], v[68:71]
	v_mfma_f32_16x16x32_bf16 v[64:67], v[156:159], v[188:191], v[64:67]
	v_mfma_f32_16x16x32_bf16 v[116:119], v[152:155], v[168:171], v[116:119]
	v_mfma_f32_16x16x32_bf16 v[112:115], v[160:163], v[168:171], v[112:115]
	v_mfma_f32_16x16x32_bf16 v[100:103], v[152:155], v[176:179], v[100:103]
	v_mfma_f32_16x16x32_bf16 v[96:99], v[160:163], v[176:179], v[96:99]
	v_mfma_f32_16x16x32_bf16 v[84:87], v[152:155], v[184:187], v[84:87]
	v_mfma_f32_16x16x32_bf16 v[80:83], v[160:163], v[184:187], v[80:83]
	v_mfma_f32_16x16x32_bf16 v[68:71], v[152:155], v[214:217], v[68:71]
	v_mfma_f32_16x16x32_bf16 v[64:67], v[160:163], v[214:217], v[64:67]
	s_setprio 0
	s_barrier
	s_add_i32 s6, s6, s25
	v_lshl_add_u64 v[198:199], s[50:51], 0, v[138:139]
	s_mov_b32 m0, s6
	ds_read_b128 v[164:167], v245 offset:16384
	ds_read_b128 v[168:171], v245 offset:17408
	ds_read_b128 v[172:175], v245 offset:18432
	ds_read_b128 v[176:179], v245 offset:19456
	ds_read_b128 v[180:183], v245 offset:20480
	ds_read_b128 v[184:187], v245 offset:21504
	ds_read_b128 v[188:191], v245 offset:22528
	ds_read_b128 v[214:217], v245 offset:23552
	global_load_lds_dwordx4 v[198:199], off
	s_add_i32 m0, s6, 0x2000
	s_add_u32 s6, s50, 0x2000
	v_lshl_add_u64 v[198:199], s[50:51], 0, v[136:137]
	s_addc_u32 s7, s51, 0
	s_add_i32 s48, s86, s25
	global_load_lds_dwordx4 v[198:199], off
	v_lshl_add_u64 v[198:199], s[6:7], 0, v[138:139]
	s_mov_b32 m0, s48
	v_lshl_add_u64 v[200:201], s[52:53], 0, v[206:207]
	global_load_lds_dwordx4 v[198:199], off
	v_lshl_add_u64 v[198:199], s[6:7], 0, v[136:137]
	s_add_i32 m0, s48, 0x2000
	s_nop 0
	global_load_lds_dwordx4 v[198:199], off
	v_lshl_add_u64 v[198:199], s[52:53], 0, v[208:209]
	s_mov_b32 m0, s12
	s_nop 0
	global_load_lds_dwordx4 v[198:199], off
	s_mov_b32 m0, s13
	s_nop 0
	global_load_lds_dwordx4 v[200:201], off
	s_waitcnt vmcnt(9)
	s_waitcnt lgkmcnt(0)
	s_barrier
	s_setprio 1
	s_waitcnt lgkmcnt(0)
	v_mfma_f32_16x16x32_bf16 v[60:63], v[128:131], v[164:167], v[60:63]
	v_mfma_f32_16x16x32_bf16 v[56:59], v[140:143], v[164:167], v[56:59]
	v_mfma_f32_16x16x32_bf16 v[44:47], v[128:131], v[172:175], v[44:47]
	v_mfma_f32_16x16x32_bf16 v[40:43], v[140:143], v[172:175], v[40:43]
	v_mfma_f32_16x16x32_bf16 v[28:31], v[128:131], v[180:183], v[28:31]
	v_mfma_f32_16x16x32_bf16 v[24:27], v[140:143], v[180:183], v[24:27]
	v_mfma_f32_16x16x32_bf16 v[12:15], v[128:131], v[188:191], v[12:15]
	v_mfma_f32_16x16x32_bf16 v[8:11], v[140:143], v[188:191], v[8:11]
	v_mfma_f32_16x16x32_bf16 v[60:63], v[132:135], v[168:171], v[60:63]
	v_mfma_f32_16x16x32_bf16 v[56:59], v[144:147], v[168:171], v[56:59]
	v_mfma_f32_16x16x32_bf16 v[44:47], v[132:135], v[176:179], v[44:47]
	v_mfma_f32_16x16x32_bf16 v[40:43], v[144:147], v[176:179], v[40:43]
	v_mfma_f32_16x16x32_bf16 v[28:31], v[132:135], v[184:187], v[28:31]
	v_mfma_f32_16x16x32_bf16 v[24:27], v[144:147], v[184:187], v[24:27]
	v_mfma_f32_16x16x32_bf16 v[12:15], v[132:135], v[214:217], v[12:15]
	v_mfma_f32_16x16x32_bf16 v[8:11], v[144:147], v[214:217], v[8:11]
	s_setprio 0
	s_setprio 1
	v_mfma_f32_16x16x32_bf16 v[52:55], v[148:151], v[164:167], v[52:55]
	v_mfma_f32_16x16x32_bf16 v[48:51], v[156:159], v[164:167], v[48:51]
	v_mfma_f32_16x16x32_bf16 v[36:39], v[148:151], v[172:175], v[36:39]
	v_mfma_f32_16x16x32_bf16 v[32:35], v[156:159], v[172:175], v[32:35]
	v_mfma_f32_16x16x32_bf16 v[20:23], v[148:151], v[180:183], v[20:23]
	v_mfma_f32_16x16x32_bf16 v[16:19], v[156:159], v[180:183], v[16:19]
	v_mfma_f32_16x16x32_bf16 v[4:7], v[148:151], v[188:191], v[4:7]
	v_mfma_f32_16x16x32_bf16 v[0:3], v[156:159], v[188:191], v[0:3]
	v_mfma_f32_16x16x32_bf16 v[52:55], v[152:155], v[168:171], v[52:55]
	v_mfma_f32_16x16x32_bf16 v[48:51], v[160:163], v[168:171], v[48:51]
	v_mfma_f32_16x16x32_bf16 v[36:39], v[152:155], v[176:179], v[36:39]
	v_mfma_f32_16x16x32_bf16 v[32:35], v[160:163], v[176:179], v[32:35]
	v_mfma_f32_16x16x32_bf16 v[20:23], v[152:155], v[184:187], v[20:23]
	v_mfma_f32_16x16x32_bf16 v[16:19], v[160:163], v[184:187], v[16:19]
	v_mfma_f32_16x16x32_bf16 v[4:7], v[152:155], v[214:217], v[4:7]
	v_mfma_f32_16x16x32_bf16 v[0:3], v[160:163], v[214:217], v[0:3]
	s_setprio 0
	s_barrier
; #define PG8_STAGE(bufoff, gbase, voff) do { _Pragma("unroll") for (int _i = 0; _i < 2; ++_i) \
;         __builtin_amdgcn_global_load_lds((const unsigned*)((const char*)(gbase) + (voff)[_i]), (LAS unsigned*)(lds + (bufoff) + ldsw + _i * 8192), 16, 0, 0); } while (0)
; #define PG8_LDA(dst, b, h) do { _Pragma("unroll") for (int m = 0; m < 4; ++m) _Pragma("unroll") for (int k = 0; k < 2; ++k) dst[m][k] = *(const LAS bf16x8*)(lds + PG8_SA(b, h) + aoff + m * 2048 + k * 1024); } while (0)
; #define PG8_LDB(dst, b, h) do { _Pragma("unroll") for (int n = 0; n < 2; ++n) _Pragma("unroll") for (int k = 0; k < 2; ++k) dst[n][k] = *(const LAS bf16x8*)(lds + PG8_SB(b, h) + boff + n * 2048 + k * 1024); } while (0)
; #define PG8_MMA(ai, bj, At, Bt) do { __builtin_amdgcn_s_setprio(1); _Pragma("unroll") for (int m = 0; m < 4; ++m) _Pragma("unroll") for (int n = 0; n < 2; ++n) _Pragma("unroll") for (int k = 0; k < 2; ++k) \
;         acc[ai][bj][m][n] = __builtin_amdgcn_mfma_f32_16x16x32_bf16(Bt[n][k], At[m][k], acc[ai][bj][m][n], 0, 0, 0); __builtin_amdgcn_s_setprio(0); } while (0)
; #define PG8_WAIT_V(n) asm volatile("s_waitcnt vmcnt(" #n ")" ::: "memory")
; #define PG8_WAIT_L(n) asm volatile("s_waitcnt lgkmcnt(" #n ")" ::: "memory")
; #define PG8_BAR __builtin_amdgcn_s_barrier()
; #define PG8_SCHED __builtin_amdgcn_sched_barrier(0)
; template <class Epi, bool ALIGN_EPI>
; __device__ __forceinline__ void gemm_phase(LAS unsigned char* lds, const Gemm g, int G, int cid, const Epi& E) {
;     ...
;             PG8_LDB(B0, 1, 0); PG8_LDB(B1, 1, 1); PG8_SCHED; PG8_LDA(At, 1, 0); PG8_STAGE(PG8_SA(0, 1), a2 + hA, voffA);
;             PG8_WAIT_V(8); PG8_WAIT_L(0); PG8_BAR; PG8_MMA(0, 0, At, B0); PG8_MMA(0, 1, At, B1); PG8_BAR; PG8_SCHED;
;             PG8_LDA(At, 1, 1); PG8_STAGE(PG8_SB(1, 0), b3, voffB); PG8_STAGE(PG8_SB(1, 1), b3 + hB, voffB); PG8_STAGE(PG8_SA(1, 0), a3, voffA);
;             PG8_WAIT_V(8); PG8_WAIT_L(0); PG8_BAR; PG8_MMA(1, 0, At, B0); PG8_MMA(1, 1, At, B1); PG8_BAR; PG8_SCHED;
	s_add_i32 s48, 0, 0x18000
	s_add_i32 s49, 0, 0x1c000
	v_add_u32_e32 v144, s48, v243
	v_add_u32_e32 v160, s49, v243
	ds_read_b128 v[128:131], v144
	ds_read_b128 v[132:135], v144 offset:1024
	ds_read_b128 v[140:143], v144 offset:2048
	ds_read_b128 v[144:147], v144 offset:3072
	ds_read_b128 v[148:151], v160
	ds_read_b128 v[152:155], v160 offset:1024
	ds_read_b128 v[156:159], v160 offset:2048
	ds_read_b128 v[160:163], v160 offset:3072
	s_add_u32 s6, s52, 0x160000
	s_addc_u32 s7, s53, 0
	s_mov_b32 m0, s54
	v_lshl_add_u64 v[218:219], s[6:7], 0, v[208:209]
	ds_read_b128 v[164:167], v245 offset:32768
	ds_read_b128 v[168:171], v245 offset:33792
	ds_read_b128 v[172:175], v245 offset:34816
	ds_read_b128 v[176:179], v245 offset:35840
	ds_read_b128 v[180:183], v245 offset:36864
	ds_read_b128 v[184:187], v245 offset:37888
	ds_read_b128 v[188:191], v245 offset:38912
	ds_read_b128 v[214:217], v245 offset:39936
	global_load_lds_dwordx4 v[218:219], off
	v_lshl_add_u64 v[218:219], s[6:7], 0, v[206:207]
	s_mov_b32 m0, s55
	s_nop 0
	global_load_lds_dwordx4 v[218:219], off
	s_waitcnt vmcnt(8)
	s_waitcnt lgkmcnt(0)
	s_barrier
	s_setprio 1
	s_waitcnt lgkmcnt(0)
	v_mfma_f32_16x16x32_bf16 v[124:127], v[128:131], v[164:167], v[124:127]
	v_mfma_f32_16x16x32_bf16 v[120:123], v[140:143], v[164:167], v[120:123]
	v_mfma_f32_16x16x32_bf16 v[108:111], v[128:131], v[172:175], v[108:111]
	v_mfma_f32_16x16x32_bf16 v[104:107], v[140:143], v[172:175], v[104:107]
	v_mfma_f32_16x16x32_bf16 v[92:95], v[128:131], v[180:183], v[92:95]
	v_mfma_f32_16x16x32_bf16 v[88:91], v[140:143], v[180:183], v[88:91]
	v_mfma_f32_16x16x32_bf16 v[76:79], v[128:131], v[188:191], v[76:79]
	v_mfma_f32_16x16x32_bf16 v[72:75], v[140:143], v[188:191], v[72:75]
	v_mfma_f32_16x16x32_bf16 v[124:127], v[132:135], v[168:171], v[124:127]
	v_mfma_f32_16x16x32_bf16 v[120:123], v[144:147], v[168:171], v[120:123]
	v_mfma_f32_16x16x32_bf16 v[108:111], v[132:135], v[176:179], v[108:111]
	v_mfma_f32_16x16x32_bf16 v[104:107], v[144:147], v[176:179], v[104:107]
	v_mfma_f32_16x16x32_bf16 v[92:95], v[132:135], v[184:187], v[92:95]
	v_mfma_f32_16x16x32_bf16 v[88:91], v[144:147], v[184:187], v[88:91]
	v_mfma_f32_16x16x32_bf16 v[76:79], v[132:135], v[214:217], v[76:79]
	v_mfma_f32_16x16x32_bf16 v[72:75], v[144:147], v[214:217], v[72:75]
	s_setprio 0
	s_setprio 1
	v_mfma_f32_16x16x32_bf16 v[116:119], v[148:151], v[164:167], v[116:119]
	v_mfma_f32_16x16x32_bf16 v[112:115], v[156:159], v[164:167], v[112:115]
	v_mfma_f32_16x16x32_bf16 v[100:103], v[148:151], v[172:175], v[100:103]
	v_mfma_f32_16x16x32_bf16 v[96:99], v[156:159], v[172:175], v[96:99]
	v_mfma_f32_16x16x32_bf16 v[84:87], v[148:151], v[180:183], v[84:87]
	v_mfma_f32_16x16x32_bf16 v[80:83], v[156:159], v[180:183], v[80:83]
	v_mfma_f32_16x16x32_bf16 v[68:71], v[148:151], v[188:191], v[68:71]
	v_mfma_f32_16x16x32_bf16 v[64:67], v[156:159], v[188:191], v[64:67]
	v_mfma_f32_16x16x32_bf16 v[116:119], v[152:155], v[168:171], v[116:119]
	v_mfma_f32_16x16x32_bf16 v[112:115], v[160:163], v[168:171], v[112:115]
	v_mfma_f32_16x16x32_bf16 v[100:103], v[152:155], v[176:179], v[100:103]
	v_mfma_f32_16x16x32_bf16 v[96:99], v[160:163], v[176:179], v[96:99]
	v_mfma_f32_16x16x32_bf16 v[84:87], v[152:155], v[184:187], v[84:87]
	v_mfma_f32_16x16x32_bf16 v[80:83], v[160:163], v[184:187], v[80:83]
	v_mfma_f32_16x16x32_bf16 v[68:71], v[152:155], v[214:217], v[68:71]
	v_mfma_f32_16x16x32_bf16 v[64:67], v[160:163], v[214:217], v[64:67]
	s_setprio 0
	s_barrier
	s_add_u32 s6, s50, 0x40000
	s_addc_u32 s7, s51, 0
	s_add_i32 s48, s48, s25
	v_lshl_add_u64 v[218:219], s[6:7], 0, v[138:139]
	s_mov_b32 m0, s48
	ds_read_b128 v[164:167], v245 offset:49152
	ds_read_b128 v[168:171], v245 offset:50176
	ds_read_b128 v[172:175], v245 offset:51200
	ds_read_b128 v[176:179], v245 offset:52224
	ds_read_b128 v[180:183], v245 offset:53248
	ds_read_b128 v[184:187], v245 offset:54272
	ds_read_b128 v[188:191], v245 offset:55296
	ds_read_b128 v[214:217], v245 offset:56320
	global_load_lds_dwordx4 v[218:219], off
	s_add_i32 m0, s48, 0x2000
	v_lshl_add_u64 v[218:219], s[6:7], 0, v[136:137]
	s_add_u32 s6, s50, 0x42000
	s_addc_u32 s7, s51, 0
	s_add_i32 s48, s49, s25
	global_load_lds_dwordx4 v[218:219], off
	v_lshl_add_u64 v[218:219], s[6:7], 0, v[138:139]
	s_mov_b32 m0, s48
	v_lshl_add_u64 v[198:199], v[198:199], 0, s[36:37]
	global_load_lds_dwordx4 v[218:219], off
	v_lshl_add_u64 v[218:219], s[6:7], 0, v[136:137]
	s_add_i32 m0, s48, 0x2000
	s_nop 0
	global_load_lds_dwordx4 v[218:219], off
	s_mov_b32 m0, s57
	s_nop 0
	global_load_lds_dwordx4 v[198:199], off
	v_lshl_add_u64 v[198:199], v[200:201], 0, s[36:37]
	s_mov_b32 m0, s58
	s_nop 0
	global_load_lds_dwordx4 v[198:199], off
	s_waitcnt vmcnt(8)
	s_waitcnt lgkmcnt(0)
	s_barrier
; __device__ __forceinline__ unsigned cvt_pk_bf16(float lo, float hi) { unsigned r; asm volatile("v_cvt_pk_bf16_f32 %0, %1, %2" : "=v"(r) : "v"(lo), "v"(hi)); return r; }
; #define PG8_WAIT_V(n) asm volatile("s_waitcnt vmcnt(" #n ")" ::: "memory")
; #define PG8_WAIT_L(n) asm volatile("s_waitcnt lgkmcnt(" #n ")" ::: "memory")
; #define PG8_BAR __builtin_amdgcn_s_barrier()
; #define PG8_SCHED __builtin_amdgcn_sched_barrier(0)
; template <class Epi, bool ALIGN_EPI>
; __device__ __forceinline__ void gemm_phase(LAS unsigned char* lds, const Gemm g, int G, int cid, const Epi& E) {
;     ...
;             PG8_WAIT_V(8); PG8_WAIT_L(0); PG8_BAR; PG8_MMA(1, 0, At, B0); PG8_MMA(1, 1, At, B1); PG8_BAR; PG8_SCHED;
;         }
;     __device__ __forceinline__ void operator()(const f32x4 (&acc)[2][2][4][2], const Unit& u, int wr, int wc, int fr, int fq, const LAS float*) const {
;     ...
;         for (int am = 0; am < NB; ++am) { const int ai = am / (NB / 2), m0 = (am % (NB / 2)) * MB;
;             f32x4 xo[4][2][2];
; #pragma unroll
;             for (int m = m0; m < m0 + MB; ++m) { const float* xr = Xs + (size_t)(row0 + ai * HALF + m * 16) * DM + col0;
; #pragma unroll
;                 for (int bj = 0; bj < 2; ++bj) { xo[m][bj][0] = *(const f32x4*)(xr + bj * HALF); xo[m][bj][1] = *(const f32x4*)(xr + bj * HALF + 4); } }
; #pragma unroll
;             for (int m = m0; m < m0 + MB; ++m) { const int row = row0 + ai * HALF + m * 16; float ss = 0.f;
;                 float* xr = X + (size_t)row * DM + col0; bf16_t* xb = XB + (size_t)row * ALD + col0;
; #pragma unroll
;                 for (int bj = 0; bj < 2; ++bj) { f32x4 x0 = xo[m][bj][0], x1 = xo[m][bj][1];
;                     if (HB) { x0 += (acc[ai][bj][m][0] + bv[bj][0]) * sv[bj][0]; x1 += (acc[ai][bj][m][1] + bv[bj][1]) * sv[bj][1]; } else { x0 += acc[ai][bj][m][0]; x1 += acc[ai][bj][m][1]; }
;                     *(f32x4*)(xr + bj * HALF) = x0; *(f32x4*)(xr + bj * HALF + 4) = x1;
;                     ss += (x0[0] * x0[0] + x0[1] * x0[1]) + (x0[2] * x0[2] + x0[3] * x0[3]) + (x1[0] * x1[0] + x1[1] * x1[1]) + (x1[2] * x1[2] + x1[3] * x1[3]);
;                     u32x4 w; w.x = cvt_pk_bf16(x0[0], x0[1]); w.y = cvt_pk_bf16(x0[2], x0[3]); w.z = cvt_pk_bf16(x1[0], x1[1]); w.w = cvt_pk_bf16(x1[2], x1[3]);
;                     if (feeds) *(u32x4*)(xb + bj * HALF) = w; }
	s_setprio 1
	s_waitcnt lgkmcnt(0)
	v_mfma_f32_16x16x32_bf16 v[60:63], v[128:131], v[164:167], v[60:63]
	v_mfma_f32_16x16x32_bf16 v[56:59], v[140:143], v[164:167], v[56:59]
	v_mfma_f32_16x16x32_bf16 v[44:47], v[128:131], v[172:175], v[44:47]
	v_mfma_f32_16x16x32_bf16 v[40:43], v[140:143], v[172:175], v[40:43]
	v_mfma_f32_16x16x32_bf16 v[28:31], v[128:131], v[180:183], v[28:31]
	v_mfma_f32_16x16x32_bf16 v[24:27], v[140:143], v[180:183], v[24:27]
	v_mfma_f32_16x16x32_bf16 v[12:15], v[128:131], v[188:191], v[12:15]
	v_mfma_f32_16x16x32_bf16 v[8:11], v[140:143], v[188:191], v[8:11]
	v_mfma_f32_16x16x32_bf16 v[60:63], v[132:135], v[168:171], v[60:63]
	v_mfma_f32_16x16x32_bf16 v[56:59], v[144:147], v[168:171], v[56:59]
	v_mfma_f32_16x16x32_bf16 v[44:47], v[132:135], v[176:179], v[44:47]
	v_mfma_f32_16x16x32_bf16 v[40:43], v[144:147], v[176:179], v[40:43]
	v_mfma_f32_16x16x32_bf16 v[28:31], v[132:135], v[184:187], v[28:31]
	v_mfma_f32_16x16x32_bf16 v[24:27], v[144:147], v[184:187], v[24:27]
	v_mfma_f32_16x16x32_bf16 v[12:15], v[132:135], v[214:217], v[12:15]
	v_mfma_f32_16x16x32_bf16 v[8:11], v[144:147], v[214:217], v[8:11]
	s_setprio 0
	s_setprio 1
	v_mfma_f32_16x16x32_bf16 v[52:55], v[148:151], v[164:167], v[52:55]
	v_mfma_f32_16x16x32_bf16 v[48:51], v[156:159], v[164:167], v[48:51]
	v_mfma_f32_16x16x32_bf16 v[36:39], v[148:151], v[172:175], v[36:39]
	v_mfma_f32_16x16x32_bf16 v[32:35], v[156:159], v[172:175], v[32:35]
	v_mfma_f32_16x16x32_bf16 v[20:23], v[148:151], v[180:183], v[20:23]
	v_mfma_f32_16x16x32_bf16 v[16:19], v[156:159], v[180:183], v[16:19]
	v_mfma_f32_16x16x32_bf16 v[4:7], v[148:151], v[188:191], v[4:7]
	v_mfma_f32_16x16x32_bf16 v[0:3], v[156:159], v[188:191], v[0:3]
	v_mfma_f32_16x16x32_bf16 v[52:55], v[152:155], v[168:171], v[52:55]
	v_mfma_f32_16x16x32_bf16 v[48:51], v[160:163], v[168:171], v[48:51]
	v_mfma_f32_16x16x32_bf16 v[36:39], v[152:155], v[176:179], v[36:39]
	v_mfma_f32_16x16x32_bf16 v[32:35], v[160:163], v[176:179], v[32:35]
	v_mfma_f32_16x16x32_bf16 v[20:23], v[152:155], v[184:187], v[20:23]
	v_mfma_f32_16x16x32_bf16 v[16:19], v[160:163], v[184:187], v[16:19]
	v_mfma_f32_16x16x32_bf16 v[4:7], v[152:155], v[214:217], v[4:7]
	v_mfma_f32_16x16x32_bf16 v[0:3], v[160:163], v[214:217], v[0:3]
	s_setprio 0
	s_barrier
	s_add_i32 s79, s79, 2
	s_add_u32 s77, s77, 0x80000
	s_addc_u32 s78, s78, 0
	s_cmpk_gt_u32 s79, 0x55
	s_mov_b64 s[48:49], s[40:41]
	s_cbranch_scc0 .LBB0_927
	v_lshl_or_b32 v214, s74, 8, v244
	v_lshl_add_u32 v216, s75, 8, v197
	v_ashrrev_i32_e32 v215, 31, v214
	v_lshlrev_b64 v[198:199], 2, v[214:215]
	v_ashrrev_i32_e32 v217, 31, v216
	v_or_b32_e32 v226, 16, v216
	v_lshl_add_u64 v[218:219], s[82:83], 0, v[198:199]
	v_lshlrev_b64 v[200:201], 13, v[216:217]
	v_ashrrev_i32_e32 v227, 31, v226
	v_or_b32_e32 v222, 32, v216
	v_or_b32_e32 v220, 48, v216
	v_lshl_add_u64 v[128:129], v[218:219], 0, v[200:201]
	v_lshlrev_b64 v[230:231], 13, v[226:227]
	v_ashrrev_i32_e32 v223, 31, v222
	v_ashrrev_i32_e32 v221, 31, v220
	global_load_dwordx4 v[188:191], v[128:129], off offset:16
	global_load_dwordx4 v[246:249], v[128:129], off
	global_load_dwordx4 v[180:183], v[128:129], off offset:528
	global_load_dwordx4 v[184:187], v[128:129], off offset:512
	v_lshl_add_u64 v[128:129], v[218:219], 0, v[230:231]
	v_lshlrev_b64 v[228:229], 13, v[222:223]
	v_lshlrev_b64 v[224:225], 13, v[220:221]
	global_load_dwordx4 v[172:175], v[128:129], off offset:16
	global_load_dwordx4 v[176:179], v[128:129], off
	global_load_dwordx4 v[164:167], v[128:129], off offset:528
	global_load_dwordx4 v[168:171], v[128:129], off offset:512
	v_lshl_add_u64 v[128:129], v[218:219], 0, v[228:229]
	v_lshl_add_u64 v[132:133], v[218:219], 0, v[224:225]
	global_load_dwordx4 v[156:159], v[128:129], off offset:16
	global_load_dwordx4 v[160:163], v[128:129], off
	global_load_dwordx4 v[148:151], v[128:129], off offset:528
	global_load_dwordx4 v[152:155], v[128:129], off offset:512
	global_load_dwordx4 v[140:143], v[132:133], off offset:16
	global_load_dwordx4 v[144:147], v[132:133], off
	s_nop 0
	global_load_dwordx4 v[128:131], v[132:133], off offset:528
	s_nop 0
	global_load_dwordx4 v[132:135], v[132:133], off offset:512
	v_lshl_add_u64 v[200:201], s[82:83], 0, v[200:201]
	v_lshl_add_u64 v[234:235], v[200:201], 0, v[198:199]
	v_mov_b64_e32 v[198:199], s[4:5]
	v_mad_i64_i32 v[198:199], s[6:7], v216, s66, v[198:199]
	v_lshl_add_u64 v[232:233], v[214:215], 1, v[198:199]
	s_and_b64 vcc, exec, s[28:29]
	s_waitcnt vmcnt(0)
	v_pk_add_f32 v[122:123], v[122:123], v[190:191]
	v_pk_add_f32 v[126:127], v[126:127], v[248:249]
	v_pk_add_f32 v[124:125], v[124:125], v[246:247]
	v_pk_add_f32 v[120:121], v[120:121], v[188:189]
	global_store_dwordx4 v[234:235], v[124:127], off
	global_store_dwordx4 v[234:235], v[120:123], off offset:16
	v_cvt_pk_bf16_f32 v188, v124, v125
	v_cvt_pk_bf16_f32 v189, v126, v127
	v_cvt_pk_bf16_f32 v190, v120, v121
	v_cvt_pk_bf16_f32 v191, v122, v123
	s_cbranch_vccz .LBB0_930
	global_store_dwordx4 v[232:233], v[188:191], off
